# plus scan carry gather: 16 predicated loads in flight instead of a serialized load-wait-write loop
# speedup vs baseline: 1.0249x; 1.0037x over previous
.LBB0_872:
	s_andn2_b64 vcc, exec, s[26:27]
	s_cbranch_vccnz .LBB0_914
	s_sub_i32 s24, s48, 64
	s_lshr_b32 s47, s24, 3
	s_and_b32 s46, s48, 7
	s_cmpk_gt_u32 s24, 0x1ff
	s_cselect_b64 s[34:35], -1, 0
	s_cmpk_lt_u32 s24, 0x200
	s_cselect_b64 s[28:29], -1, 0
	s_and_b64 s[30:31], s[28:29], exec
	v_mov_b32_e32 v24, v200
	s_mov_b32 s30, 0x1ffffffc
	s_load_dwordx2 s[26:27], s[22:23], 0x110
	s_cselect_b32 s30, s30, 0x1fffffc0
	s_cselect_b32 s31, 3, 63
	s_and_b32 s52, s30, s47
	s_or_b32 s36, s31, s47
	s_sub_i32 s44, s36, s52
	v_and_b32_e32 v72, 0xff, v24
	s_lshl_b32 s53, s44, 6
	v_and_b32_e32 v71, 63, v24
	v_bfe_u32 v70, v24, 6, 2
	s_sub_i32 s45, s47, s52
	v_cmp_gt_i32_e32 vcc, s53, v72
	s_and_saveexec_b64 s[30:31], vcc
	s_cbranch_execz .LBB0_878
	s_lshr_b32 s37, s49, 3
	s_lshl_b32 s42, s46, 9
	s_waitcnt lgkmcnt(0)
	s_add_u32 s42, s26, s42
	s_addc_u32 s43, s27, 0
	s_add_i32 s36, s36, s37
	v_lshlrev_b32_e32 v2, 3, v71
	s_sub_i32 s36, s36, s52
	v_lshl_add_u64 v[0:1], s[42:43], 0, v[2:3]
	s_mov_b64 s[42:43], 0x2f88000
	v_sub_u32_e32 v4, s36, v70
	v_lshl_add_u64 v[0:1], v[0:1], 0, s[42:43]
	v_lshl_add_u32 v2, v72, 3, s51
	v_lshl_or_b32 v6, v4, 1, 1
	s_mov_b64 s[36:37], 0
	v_mov_b32_e32 v7, v70
	v_mov_b32_e32 v8, v72
	s_mov_b64 s[36:37], exec
	v_add_u32_e32 v9, 0, v70
	v_cmp_gt_i32_e32 vcc, s45, v9
	v_add_lshl_u32 v10, v9, s52, 1
	v_add_u32_e32 v11, 0, v6
	v_cndmask_b32_e32 v10, v11, v10, vcc
	v_ashrrev_i32_e32 v11, 31, v10
	v_lshlrev_b64 v[10:11], 12, v[10:11]
	v_lshl_add_u64 v[10:11], v[0:1], 0, v[10:11]
	global_load_dwordx2 v[80:81], v[10:11], off
	v_add_u32_e32 v12, 256, v72
	v_cmp_gt_i32_e32 vcc, s53, v12
	s_and_b64 exec, exec, vcc
	s_cbranch_execz .Lsg_loaded
	v_add_u32_e32 v9, 4, v70
	v_cmp_gt_i32_e32 vcc, s45, v9
	v_add_lshl_u32 v10, v9, s52, 1
	v_add_u32_e32 v11, -8, v6
	v_cndmask_b32_e32 v10, v11, v10, vcc
	v_ashrrev_i32_e32 v11, 31, v10
	v_lshlrev_b64 v[10:11], 12, v[10:11]
	v_lshl_add_u64 v[10:11], v[0:1], 0, v[10:11]
	global_load_dwordx2 v[82:83], v[10:11], off
	v_add_u32_e32 v12, 512, v72
	v_cmp_gt_i32_e32 vcc, s53, v12
	s_and_b64 exec, exec, vcc
	s_cbranch_execz .Lsg_loaded
	v_add_u32_e32 v9, 8, v70
	v_cmp_gt_i32_e32 vcc, s45, v9
	v_add_lshl_u32 v10, v9, s52, 1
	v_add_u32_e32 v11, -16, v6
	v_cndmask_b32_e32 v10, v11, v10, vcc
	v_ashrrev_i32_e32 v11, 31, v10
	v_lshlrev_b64 v[10:11], 12, v[10:11]
	v_lshl_add_u64 v[10:11], v[0:1], 0, v[10:11]
	global_load_dwordx2 v[84:85], v[10:11], off
	v_add_u32_e32 v12, 768, v72
	v_cmp_gt_i32_e32 vcc, s53, v12
	s_and_b64 exec, exec, vcc
	s_cbranch_execz .Lsg_loaded
	v_add_u32_e32 v9, 12, v70
	v_cmp_gt_i32_e32 vcc, s45, v9
	v_add_lshl_u32 v10, v9, s52, 1
	v_add_u32_e32 v11, -24, v6
	v_cndmask_b32_e32 v10, v11, v10, vcc
	v_ashrrev_i32_e32 v11, 31, v10
	v_lshlrev_b64 v[10:11], 12, v[10:11]
	v_lshl_add_u64 v[10:11], v[0:1], 0, v[10:11]
	global_load_dwordx2 v[86:87], v[10:11], off
	v_add_u32_e32 v12, 1024, v72
	v_cmp_gt_i32_e32 vcc, s53, v12
	s_and_b64 exec, exec, vcc
	s_cbranch_execz .Lsg_loaded
	v_add_u32_e32 v9, 16, v70
	v_cmp_gt_i32_e32 vcc, s45, v9
	v_add_lshl_u32 v10, v9, s52, 1
	v_add_u32_e32 v11, -32, v6
	v_cndmask_b32_e32 v10, v11, v10, vcc
	v_ashrrev_i32_e32 v11, 31, v10
	v_lshlrev_b64 v[10:11], 12, v[10:11]
	v_lshl_add_u64 v[10:11], v[0:1], 0, v[10:11]
	global_load_dwordx2 v[88:89], v[10:11], off
	v_add_u32_e32 v12, 1280, v72
	v_cmp_gt_i32_e32 vcc, s53, v12
	s_and_b64 exec, exec, vcc
	s_cbranch_execz .Lsg_loaded
	v_add_u32_e32 v9, 20, v70
	v_cmp_gt_i32_e32 vcc, s45, v9
	v_add_lshl_u32 v10, v9, s52, 1
	v_add_u32_e32 v11, -40, v6
	v_cndmask_b32_e32 v10, v11, v10, vcc
	v_ashrrev_i32_e32 v11, 31, v10
	v_lshlrev_b64 v[10:11], 12, v[10:11]
	v_lshl_add_u64 v[10:11], v[0:1], 0, v[10:11]
	global_load_dwordx2 v[90:91], v[10:11], off
	v_add_u32_e32 v12, 1536, v72
	v_cmp_gt_i32_e32 vcc, s53, v12
	s_and_b64 exec, exec, vcc
	s_cbranch_execz .Lsg_loaded
	v_add_u32_e32 v9, 24, v70
	v_cmp_gt_i32_e32 vcc, s45, v9
	v_add_lshl_u32 v10, v9, s52, 1
	v_add_u32_e32 v11, -48, v6
	v_cndmask_b32_e32 v10, v11, v10, vcc
	v_ashrrev_i32_e32 v11, 31, v10
	v_lshlrev_b64 v[10:11], 12, v[10:11]
	v_lshl_add_u64 v[10:11], v[0:1], 0, v[10:11]
	global_load_dwordx2 v[92:93], v[10:11], off
	v_add_u32_e32 v12, 1792, v72
	v_cmp_gt_i32_e32 vcc, s53, v12
	s_and_b64 exec, exec, vcc
	s_cbranch_execz .Lsg_loaded
	v_add_u32_e32 v9, 28, v70
	v_cmp_gt_i32_e32 vcc, s45, v9
	v_add_lshl_u32 v10, v9, s52, 1
	v_add_u32_e32 v11, -56, v6
	v_cndmask_b32_e32 v10, v11, v10, vcc
	v_ashrrev_i32_e32 v11, 31, v10
	v_lshlrev_b64 v[10:11], 12, v[10:11]
	v_lshl_add_u64 v[10:11], v[0:1], 0, v[10:11]
	global_load_dwordx2 v[94:95], v[10:11], off
	v_add_u32_e32 v12, 2048, v72
	v_cmp_gt_i32_e32 vcc, s53, v12
	s_and_b64 exec, exec, vcc
	s_cbranch_execz .Lsg_loaded
	v_add_u32_e32 v9, 32, v70
	v_cmp_gt_i32_e32 vcc, s45, v9
	v_add_lshl_u32 v10, v9, s52, 1
	v_add_u32_e32 v11, -64, v6
	v_cndmask_b32_e32 v10, v11, v10, vcc
	v_ashrrev_i32_e32 v11, 31, v10
	v_lshlrev_b64 v[10:11], 12, v[10:11]
	v_lshl_add_u64 v[10:11], v[0:1], 0, v[10:11]
	global_load_dwordx2 v[96:97], v[10:11], off
	v_add_u32_e32 v12, 2304, v72
	v_cmp_gt_i32_e32 vcc, s53, v12
	s_and_b64 exec, exec, vcc
	s_cbranch_execz .Lsg_loaded
	v_add_u32_e32 v9, 36, v70
	v_cmp_gt_i32_e32 vcc, s45, v9
	v_add_lshl_u32 v10, v9, s52, 1
	v_add_u32_e32 v11, -72, v6
	v_cndmask_b32_e32 v10, v11, v10, vcc
	v_ashrrev_i32_e32 v11, 31, v10
	v_lshlrev_b64 v[10:11], 12, v[10:11]
	v_lshl_add_u64 v[10:11], v[0:1], 0, v[10:11]
	global_load_dwordx2 v[98:99], v[10:11], off
	v_add_u32_e32 v12, 2560, v72
	v_cmp_gt_i32_e32 vcc, s53, v12
	s_and_b64 exec, exec, vcc
	s_cbranch_execz .Lsg_loaded
	v_add_u32_e32 v9, 40, v70
	v_cmp_gt_i32_e32 vcc, s45, v9
	v_add_lshl_u32 v10, v9, s52, 1
	v_add_u32_e32 v11, -80, v6
	v_cndmask_b32_e32 v10, v11, v10, vcc
	v_ashrrev_i32_e32 v11, 31, v10
	v_lshlrev_b64 v[10:11], 12, v[10:11]
	v_lshl_add_u64 v[10:11], v[0:1], 0, v[10:11]
	global_load_dwordx2 v[100:101], v[10:11], off
	v_add_u32_e32 v12, 2816, v72
	v_cmp_gt_i32_e32 vcc, s53, v12
	s_and_b64 exec, exec, vcc
	s_cbranch_execz .Lsg_loaded
	v_add_u32_e32 v9, 44, v70
	v_cmp_gt_i32_e32 vcc, s45, v9
	v_add_lshl_u32 v10, v9, s52, 1
	v_add_u32_e32 v11, -88, v6
	v_cndmask_b32_e32 v10, v11, v10, vcc
	v_ashrrev_i32_e32 v11, 31, v10
	v_lshlrev_b64 v[10:11], 12, v[10:11]
	v_lshl_add_u64 v[10:11], v[0:1], 0, v[10:11]
	global_load_dwordx2 v[102:103], v[10:11], off
	v_add_u32_e32 v12, 3072, v72
	v_cmp_gt_i32_e32 vcc, s53, v12
	s_and_b64 exec, exec, vcc
	s_cbranch_execz .Lsg_loaded
	v_add_u32_e32 v9, 48, v70
	v_cmp_gt_i32_e32 vcc, s45, v9
	v_add_lshl_u32 v10, v9, s52, 1
	v_add_u32_e32 v11, -96, v6
	v_cndmask_b32_e32 v10, v11, v10, vcc
	v_ashrrev_i32_e32 v11, 31, v10
	v_lshlrev_b64 v[10:11], 12, v[10:11]
	v_lshl_add_u64 v[10:11], v[0:1], 0, v[10:11]
	global_load_dwordx2 v[104:105], v[10:11], off
	v_add_u32_e32 v12, 3328, v72
	v_cmp_gt_i32_e32 vcc, s53, v12
	s_and_b64 exec, exec, vcc
	s_cbranch_execz .Lsg_loaded
	v_add_u32_e32 v9, 52, v70
	v_cmp_gt_i32_e32 vcc, s45, v9
	v_add_lshl_u32 v10, v9, s52, 1
	v_add_u32_e32 v11, -104, v6
	v_cndmask_b32_e32 v10, v11, v10, vcc
	v_ashrrev_i32_e32 v11, 31, v10
	v_lshlrev_b64 v[10:11], 12, v[10:11]
	v_lshl_add_u64 v[10:11], v[0:1], 0, v[10:11]
	global_load_dwordx2 v[106:107], v[10:11], off
	v_add_u32_e32 v12, 3584, v72
	v_cmp_gt_i32_e32 vcc, s53, v12
	s_and_b64 exec, exec, vcc
	s_cbranch_execz .Lsg_loaded
	v_add_u32_e32 v9, 56, v70
	v_cmp_gt_i32_e32 vcc, s45, v9
	v_add_lshl_u32 v10, v9, s52, 1
	v_add_u32_e32 v11, -112, v6
	v_cndmask_b32_e32 v10, v11, v10, vcc
	v_ashrrev_i32_e32 v11, 31, v10
	v_lshlrev_b64 v[10:11], 12, v[10:11]
	v_lshl_add_u64 v[10:11], v[0:1], 0, v[10:11]
	global_load_dwordx2 v[108:109], v[10:11], off
	v_add_u32_e32 v12, 3840, v72
	v_cmp_gt_i32_e32 vcc, s53, v12
	s_and_b64 exec, exec, vcc
	s_cbranch_execz .Lsg_loaded
	v_add_u32_e32 v9, 60, v70
	v_cmp_gt_i32_e32 vcc, s45, v9
	v_add_lshl_u32 v10, v9, s52, 1
	v_add_u32_e32 v11, -120, v6
	v_cndmask_b32_e32 v10, v11, v10, vcc
	v_ashrrev_i32_e32 v11, 31, v10
	v_lshlrev_b64 v[10:11], 12, v[10:11]
	v_lshl_add_u64 v[10:11], v[0:1], 0, v[10:11]
	global_load_dwordx2 v[110:111], v[10:11], off
.Lsg_loaded:
	s_mov_b64 exec, s[36:37]
	s_waitcnt vmcnt(0)
	ds_write_b64 v2, v[80:81]
	v_add_u32_e32 v12, 256, v72
	v_cmp_gt_i32_e32 vcc, s53, v12
	s_and_b64 exec, exec, vcc
	s_cbranch_execz .LBB0_878
	ds_write_b64 v2, v[82:83] offset:2048
	v_add_u32_e32 v12, 512, v72
	v_cmp_gt_i32_e32 vcc, s53, v12
	s_and_b64 exec, exec, vcc
	s_cbranch_execz .LBB0_878
	ds_write_b64 v2, v[84:85] offset:4096
	v_add_u32_e32 v12, 768, v72
	v_cmp_gt_i32_e32 vcc, s53, v12
	s_and_b64 exec, exec, vcc
	s_cbranch_execz .LBB0_878
	ds_write_b64 v2, v[86:87] offset:6144
	v_add_u32_e32 v12, 1024, v72
	v_cmp_gt_i32_e32 vcc, s53, v12
	s_and_b64 exec, exec, vcc
	s_cbranch_execz .LBB0_878
	ds_write_b64 v2, v[88:89] offset:8192
	v_add_u32_e32 v12, 1280, v72
	v_cmp_gt_i32_e32 vcc, s53, v12
	s_and_b64 exec, exec, vcc
	s_cbranch_execz .LBB0_878
	ds_write_b64 v2, v[90:91] offset:10240
	v_add_u32_e32 v12, 1536, v72
	v_cmp_gt_i32_e32 vcc, s53, v12
	s_and_b64 exec, exec, vcc
	s_cbranch_execz .LBB0_878
	ds_write_b64 v2, v[92:93] offset:12288
	v_add_u32_e32 v12, 1792, v72
	v_cmp_gt_i32_e32 vcc, s53, v12
	s_and_b64 exec, exec, vcc
	s_cbranch_execz .LBB0_878
	ds_write_b64 v2, v[94:95] offset:14336
	v_add_u32_e32 v12, 2048, v72
	v_cmp_gt_i32_e32 vcc, s53, v12
	s_and_b64 exec, exec, vcc
	s_cbranch_execz .LBB0_878
	ds_write_b64 v2, v[96:97] offset:16384
	v_add_u32_e32 v12, 2304, v72
	v_cmp_gt_i32_e32 vcc, s53, v12
	s_and_b64 exec, exec, vcc
	s_cbranch_execz .LBB0_878
	ds_write_b64 v2, v[98:99] offset:18432
	v_add_u32_e32 v12, 2560, v72
	v_cmp_gt_i32_e32 vcc, s53, v12
	s_and_b64 exec, exec, vcc
	s_cbranch_execz .LBB0_878
	ds_write_b64 v2, v[100:101] offset:20480
	v_add_u32_e32 v12, 2816, v72
	v_cmp_gt_i32_e32 vcc, s53, v12
	s_and_b64 exec, exec, vcc
	s_cbranch_execz .LBB0_878
	ds_write_b64 v2, v[102:103] offset:22528
	v_add_u32_e32 v12, 3072, v72
	v_cmp_gt_i32_e32 vcc, s53, v12
	s_and_b64 exec, exec, vcc
	s_cbranch_execz .LBB0_878
	ds_write_b64 v2, v[104:105] offset:24576
	v_add_u32_e32 v12, 3328, v72
	v_cmp_gt_i32_e32 vcc, s53, v12
	s_and_b64 exec, exec, vcc
	s_cbranch_execz .LBB0_878
	ds_write_b64 v2, v[106:107] offset:26624
	v_add_u32_e32 v12, 3584, v72
	v_cmp_gt_i32_e32 vcc, s53, v12
	s_and_b64 exec, exec, vcc
	s_cbranch_execz .LBB0_878
	ds_write_b64 v2, v[108:109] offset:28672
	v_add_u32_e32 v12, 3840, v72
	v_cmp_gt_i32_e32 vcc, s53, v12
	s_and_b64 exec, exec, vcc
	s_cbranch_execz .LBB0_878
	ds_write_b64 v2, v[110:111] offset:30720
